# conversion-loop weight stores sc1 nt (streaming) instead of sc1
# baseline (speedup 1.0000x reference)
; #define LAS __attribute__((address_space(3)))
; __device__ __forceinline__ void tr_item_cu(const float* __restrict__ W, int K, int N, bf16* __restrict__ WT, const float* rowgain, int mode, LAS unsigned char* buf, int item, int wave, int lane) {
;     ...
;     for (int m = 0; m < 8; ++m) { const int row = 16 * wave + 2 * m + hr;
;         const u32x4 o = *(const LAS u32x4*)(buf + row * TCP + c * 16);
;         asm volatile("global_store_dwordx4 %0, %1, off sc1\n\ts_nop 1" :: "v"(WT + (size_t)row_map(mode, n0 + row) * K + k0 + 8 * c), "v"(o) : "memory"); }
; __global__ void __launch_bounds__(NTHREADS, 2) mega_fwd(Args args) {
;     ...
;         for (int it = bid; it < DEPTH * I_LAYER; it += G, nbuf ^= 1) {
;             const int itr = DEPTH * I_LAYER - 1 - it;
;             const int l = itr / I_LAYER; int r = itr - l * I_LAYER;
;             unsigned char* WL = P_WL(l);
;             const float* W; int K, N, mode = 0; bf16* WT; const float* rg = nullptr;
;             if (r < 3 * I_GU) { const int w = r / I_GU; r -= w * I_GU;
;                 if (w < 2) { W = args.in[2 + w] + (size_t)l * D * FF; K = D; N = FF; WT = (bf16*)(WL + OFF_WGU1); rg = args.in[1] + (size_t)l * D; mode = 1 + w; }
;                 else { W = args.in[4] + (size_t)l * FF * D; K = FF; N = D; WT = (bf16*)(WL + OFF_WD1); } }
;             else if ((r -= 3 * I_GU) < 3 * I_GU) { const int w = r / I_GU; r -= w * I_GU;
;                 if (w < 2) { W = args.in[13 + w] + (size_t)l * D * FF; K = D; N = FF; WT = (bf16*)(WL + OFF_WGU2); rg = args.in[12] + (size_t)l * D; mode = 1 + w; }
;                 else { W = args.in[15] + (size_t)l * FF * D; K = FF; N = D; WT = (bf16*)(WL + OFF_WD2); } }
;             else if ((r -= 3 * I_GU) < I_IN) { W = args.in[6] + (size_t)l * D * INW; K = D; N = INW; WT = (bf16*)(WL + OFF_WIN); rg = args.in[5] + (size_t)l * D; mode = 3; }
;             else { r -= I_IN; W = args.in[11] + (size_t)l * D * D; K = D; N = D; WT = (bf16*)(WL + OFF_WOUT); }
;             tr_item_cu(W, K, N, WT, rg, mode, lds + nbuf * TC_BUF, r, wave, lane);
;         }
.LBB0_32:
	v_ashrrev_i32_e32 v8, 31, v9
	v_mul_lo_u32 v10, s21, v9
	v_mul_lo_u32 v11, s20, v8
	v_mad_u64_u32 v[8:9], s[20:21], s20, v9, 0
	s_load_dwordx4 s[20:23], s[0:1], 0x88
	v_add3_u32 v9, v9, v11, v10
	v_lshl_add_u64 v[6:7], v[8:9], 1, v[6:7]
	s_waitcnt lgkmcnt(0)
	global_store_dwordx4 v[6:7], v[48:51], off sc1 nt
	s_nop 1
	s_xor_b32 s43, s43, 1
	s_add_i32 s44, s44, s100
	s_sub_i32 s38, s38, s100
	s_sub_i32 s39, s39, s100
	s_mov_b32 s100, s99
	s_cmp_gt_i32 s44, s101
	s_cbranch_scc1 .LBB0_184

; #define LAS __attribute__((address_space(3)))
; __device__ __forceinline__ int row_map(int mode, int n) {
;     if (mode == 0) return n;
;     if (mode == 1) return (n >> 7) * 256 + (n & 127);
;     if (mode == 2) return (n >> 7) * 256 + 128 + (n & 127);
;     if (n < 1024 || n >= 3072) { const int c = n & 31; return (n & ~31) + 16 * ((c >> 2) & 1) + 4 * (c >> 3) + (c & 3); }
;     const int dd = (n - 1024) & 127; return (n - dd) + ((((dd >> 4) & 3) << 5) | ((dd >> 6) << 4) | (dd & 15));
; __device__ __forceinline__ void tr_item_cu(const float* __restrict__ W, int K, int N, bf16* __restrict__ WT, const float* rowgain, int mode, LAS unsigned char* buf, int item, int wave, int lane) {
;     ...
;     for (int m = 0; m < 8; ++m) { const int row = 16 * wave + 2 * m + hr;
;         const u32x4 o = *(const LAS u32x4*)(buf + row * TCP + c * 16);
;         asm volatile("global_store_dwordx4 %0, %1, off sc1\n\ts_nop 1" :: "v"(WT + (size_t)row_map(mode, n0 + row) * K + k0 + 8 * c), "v"(o) : "memory"); }
.LBB0_73:
	s_lshl_b64 s[26:27], s[26:27], 1
	s_add_u32 s24, s24, s26
	s_addc_u32 s25, s25, s27
	v_ashrrev_i32_e32 v10, 31, v9
	v_lshl_add_u64 v[6:7], s[24:25], 0, v[68:69]
	v_mul_lo_u32 v12, s21, v9
	v_mul_lo_u32 v13, s20, v10
	v_mad_u64_u32 v[10:11], s[24:25], s20, v9, 0
	v_add3_u32 v11, v11, v13, v12
	v_lshl_add_u64 v[10:11], v[10:11], 1, v[6:7]
	s_waitcnt lgkmcnt(0)
	global_store_dwordx4 v[10:11], v[20:23], off sc1 nt
	s_nop 1
	s_cmp_lt_i32 s45, 1
	v_add_u32_e32 v9, s22, v82
	s_cbranch_scc1 .LBB0_78
	s_cmp_gt_i32 s45, 1
	s_cbranch_scc0 .LBB0_79
	s_cmp_eq_u32 s45, 2
	s_mov_b64 s[24:25], -1
	s_cbranch_scc0 .LBB0_77
	v_lshlrev_b32_e32 v10, 1, v9
	v_and_or_b32 v10, v10, s40, v110
	s_mov_b64 s[24:25], 0

; #define LAS __attribute__((address_space(3)))
; __device__ __forceinline__ int row_map(int mode, int n) {
;     if (mode == 0) return n;
;     if (mode == 1) return (n >> 7) * 256 + (n & 127);
;     if (mode == 2) return (n >> 7) * 256 + 128 + (n & 127);
;     if (n < 1024 || n >= 3072) { const int c = n & 31; return (n & ~31) + 16 * ((c >> 2) & 1) + 4 * (c >> 3) + (c & 3); }
;     const int dd = (n - 1024) & 127; return (n - dd) + ((((dd >> 4) & 3) << 5) | ((dd >> 6) << 4) | (dd & 15));
; __device__ __forceinline__ void tr_item_cu(const float* __restrict__ W, int K, int N, bf16* __restrict__ WT, const float* rowgain, int mode, LAS unsigned char* buf, int item, int wave, int lane) {
;     ...
;     for (int m = 0; m < 8; ++m) { const int row = 16 * wave + 2 * m + hr;
;         const u32x4 o = *(const LAS u32x4*)(buf + row * TCP + c * 16);
;         asm volatile("global_store_dwordx4 %0, %1, off sc1\n\ts_nop 1" :: "v"(WT + (size_t)row_map(mode, n0 + row) * K + k0 + 8 * c), "v"(o) : "memory"); }
.LBB0_89:
	v_ashrrev_i32_e32 v9, 31, v10
	v_mul_lo_u32 v12, s21, v10
	v_mul_lo_u32 v9, s20, v9
	v_mad_u64_u32 v[10:11], s[24:25], s20, v10, 0
	v_add3_u32 v11, v11, v9, v12
	v_lshl_add_u64 v[10:11], v[10:11], 1, v[6:7]
	s_waitcnt lgkmcnt(0)
	global_store_dwordx4 v[10:11], v[24:27], off sc1 nt
	s_nop 1
	s_cmp_lt_i32 s45, 1
	v_add_u32_e32 v9, s22, v86
	s_cbranch_scc1 .LBB0_94
	s_cmp_gt_i32 s45, 1
	s_cbranch_scc0 .LBB0_95
	s_cmp_eq_u32 s45, 2
	s_mov_b64 s[24:25], -1
	s_cbranch_scc0 .LBB0_93
	v_lshlrev_b32_e32 v10, 1, v9
	v_and_or_b32 v10, v10, s40, v111
	s_mov_b64 s[24:25], 0

; #define LAS __attribute__((address_space(3)))
; __device__ __forceinline__ int row_map(int mode, int n) {
;     if (mode == 0) return n;
;     if (mode == 1) return (n >> 7) * 256 + (n & 127);
;     if (mode == 2) return (n >> 7) * 256 + 128 + (n & 127);
;     if (n < 1024 || n >= 3072) { const int c = n & 31; return (n & ~31) + 16 * ((c >> 2) & 1) + 4 * (c >> 3) + (c & 3); }
;     const int dd = (n - 1024) & 127; return (n - dd) + ((((dd >> 4) & 3) << 5) | ((dd >> 6) << 4) | (dd & 15));
; __device__ __forceinline__ void tr_item_cu(const float* __restrict__ W, int K, int N, bf16* __restrict__ WT, const float* rowgain, int mode, LAS unsigned char* buf, int item, int wave, int lane) {
;     ...
;     for (int m = 0; m < 8; ++m) { const int row = 16 * wave + 2 * m + hr;
;         const u32x4 o = *(const LAS u32x4*)(buf + row * TCP + c * 16);
;         asm volatile("global_store_dwordx4 %0, %1, off sc1\n\ts_nop 1" :: "v"(WT + (size_t)row_map(mode, n0 + row) * K + k0 + 8 * c), "v"(o) : "memory"); }
.LBB0_105:
	v_ashrrev_i32_e32 v9, 31, v10
	v_mul_lo_u32 v12, s21, v10
	v_mul_lo_u32 v9, s20, v9
	v_mad_u64_u32 v[10:11], s[24:25], s20, v10, 0
	v_add3_u32 v11, v11, v9, v12
	v_lshl_add_u64 v[10:11], v[10:11], 1, v[6:7]
	s_waitcnt lgkmcnt(0)
	global_store_dwordx4 v[10:11], v[28:31], off sc1 nt
	s_nop 1
	s_cmp_lt_i32 s45, 1
	v_add_u32_e32 v9, s22, v90
	s_cbranch_scc1 .LBB0_110
	s_cmp_gt_i32 s45, 1
	s_cbranch_scc0 .LBB0_111
	s_cmp_eq_u32 s45, 2
	s_mov_b64 s[24:25], -1
	s_cbranch_scc0 .LBB0_109
	v_lshlrev_b32_e32 v10, 1, v9
	v_and_or_b32 v10, v10, s40, v112
	s_mov_b64 s[24:25], 0

; #define LAS __attribute__((address_space(3)))
; __device__ __forceinline__ int row_map(int mode, int n) {
;     if (mode == 0) return n;
;     if (mode == 1) return (n >> 7) * 256 + (n & 127);
;     if (mode == 2) return (n >> 7) * 256 + 128 + (n & 127);
;     if (n < 1024 || n >= 3072) { const int c = n & 31; return (n & ~31) + 16 * ((c >> 2) & 1) + 4 * (c >> 3) + (c & 3); }
;     const int dd = (n - 1024) & 127; return (n - dd) + ((((dd >> 4) & 3) << 5) | ((dd >> 6) << 4) | (dd & 15));
; __device__ __forceinline__ void tr_item_cu(const float* __restrict__ W, int K, int N, bf16* __restrict__ WT, const float* rowgain, int mode, LAS unsigned char* buf, int item, int wave, int lane) {
;     ...
;     for (int m = 0; m < 8; ++m) { const int row = 16 * wave + 2 * m + hr;
;         const u32x4 o = *(const LAS u32x4*)(buf + row * TCP + c * 16);
;         asm volatile("global_store_dwordx4 %0, %1, off sc1\n\ts_nop 1" :: "v"(WT + (size_t)row_map(mode, n0 + row) * K + k0 + 8 * c), "v"(o) : "memory"); }
.LBB0_121:
	v_ashrrev_i32_e32 v9, 31, v10
	v_mul_lo_u32 v12, s21, v10
	v_mul_lo_u32 v9, s20, v9
	v_mad_u64_u32 v[10:11], s[24:25], s20, v10, 0
	v_add3_u32 v11, v11, v9, v12
	v_lshl_add_u64 v[10:11], v[10:11], 1, v[6:7]
	s_waitcnt lgkmcnt(0)
	global_store_dwordx4 v[10:11], v[32:35], off sc1 nt
	s_nop 1
	s_cmp_lt_i32 s45, 1
	v_add_u32_e32 v9, s22, v94
	s_cbranch_scc1 .LBB0_126
	s_cmp_gt_i32 s45, 1
	s_cbranch_scc0 .LBB0_127
	s_cmp_eq_u32 s45, 2
	s_mov_b64 s[24:25], -1
	s_cbranch_scc0 .LBB0_125
	v_lshlrev_b32_e32 v10, 1, v9
	v_and_or_b32 v10, v10, s40, v113
	s_mov_b64 s[24:25], 0

; #define LAS __attribute__((address_space(3)))
; __device__ __forceinline__ int row_map(int mode, int n) {
;     if (mode == 0) return n;
;     if (mode == 1) return (n >> 7) * 256 + (n & 127);
;     if (mode == 2) return (n >> 7) * 256 + 128 + (n & 127);
;     if (n < 1024 || n >= 3072) { const int c = n & 31; return (n & ~31) + 16 * ((c >> 2) & 1) + 4 * (c >> 3) + (c & 3); }
;     const int dd = (n - 1024) & 127; return (n - dd) + ((((dd >> 4) & 3) << 5) | ((dd >> 6) << 4) | (dd & 15));
; __device__ __forceinline__ void tr_item_cu(const float* __restrict__ W, int K, int N, bf16* __restrict__ WT, const float* rowgain, int mode, LAS unsigned char* buf, int item, int wave, int lane) {
;     ...
;     for (int m = 0; m < 8; ++m) { const int row = 16 * wave + 2 * m + hr;
;         const u32x4 o = *(const LAS u32x4*)(buf + row * TCP + c * 16);
;         asm volatile("global_store_dwordx4 %0, %1, off sc1\n\ts_nop 1" :: "v"(WT + (size_t)row_map(mode, n0 + row) * K + k0 + 8 * c), "v"(o) : "memory"); }
.LBB0_137:
	v_ashrrev_i32_e32 v9, 31, v10
	v_mul_lo_u32 v12, s21, v10
	v_mul_lo_u32 v9, s20, v9
	v_mad_u64_u32 v[10:11], s[24:25], s20, v10, 0
	v_add3_u32 v11, v11, v9, v12
	v_lshl_add_u64 v[10:11], v[10:11], 1, v[6:7]
	s_waitcnt lgkmcnt(0)
	global_store_dwordx4 v[10:11], v[36:39], off sc1 nt
	s_nop 1
	s_cmp_lt_i32 s45, 1
	v_add_u32_e32 v9, s22, v97
	s_cbranch_scc1 .LBB0_142
	s_cmp_gt_i32 s45, 1
	s_cbranch_scc0 .LBB0_143
	s_cmp_eq_u32 s45, 2
	s_mov_b64 s[24:25], -1
	s_cbranch_scc0 .LBB0_141
	v_lshlrev_b32_e32 v10, 1, v9
	v_and_or_b32 v10, v10, s40, v114
	s_mov_b64 s[24:25], 0

; #define LAS __attribute__((address_space(3)))
; __device__ __forceinline__ int row_map(int mode, int n) {
;     if (mode == 0) return n;
;     if (mode == 1) return (n >> 7) * 256 + (n & 127);
;     if (mode == 2) return (n >> 7) * 256 + 128 + (n & 127);
;     if (n < 1024 || n >= 3072) { const int c = n & 31; return (n & ~31) + 16 * ((c >> 2) & 1) + 4 * (c >> 3) + (c & 3); }
;     const int dd = (n - 1024) & 127; return (n - dd) + ((((dd >> 4) & 3) << 5) | ((dd >> 6) << 4) | (dd & 15));
; __device__ __forceinline__ void tr_item_cu(const float* __restrict__ W, int K, int N, bf16* __restrict__ WT, const float* rowgain, int mode, LAS unsigned char* buf, int item, int wave, int lane) {
;     ...
;     for (int m = 0; m < 8; ++m) { const int row = 16 * wave + 2 * m + hr;
;         const u32x4 o = *(const LAS u32x4*)(buf + row * TCP + c * 16);
;         asm volatile("global_store_dwordx4 %0, %1, off sc1\n\ts_nop 1" :: "v"(WT + (size_t)row_map(mode, n0 + row) * K + k0 + 8 * c), "v"(o) : "memory"); }
.LBB0_153:
	v_ashrrev_i32_e32 v9, 31, v10
	v_mul_lo_u32 v12, s21, v10
	v_mul_lo_u32 v9, s20, v9
	v_mad_u64_u32 v[10:11], s[24:25], s20, v10, 0
	v_add3_u32 v11, v11, v9, v12
	v_lshl_add_u64 v[10:11], v[10:11], 1, v[6:7]
	s_waitcnt lgkmcnt(0)
	global_store_dwordx4 v[10:11], v[40:43], off sc1 nt
	s_nop 1
	s_cmp_lt_i32 s45, 1
	v_add_u32_e32 v9, s22, v101
	s_cbranch_scc1 .LBB0_158
	s_cmp_gt_i32 s45, 1
	s_cbranch_scc0 .LBB0_159
	s_cmp_eq_u32 s45, 2
	s_mov_b64 s[24:25], -1
	s_cbranch_scc0 .LBB0_157
	v_lshlrev_b32_e32 v10, 1, v9
	v_and_or_b32 v10, v10, s40, v115
	s_mov_b64 s[24:25], 0

; #define LAS __attribute__((address_space(3)))
; __device__ __forceinline__ int row_map(int mode, int n) {
;     if (mode == 0) return n;
;     if (mode == 1) return (n >> 7) * 256 + (n & 127);
;     if (mode == 2) return (n >> 7) * 256 + 128 + (n & 127);
;     if (n < 1024 || n >= 3072) { const int c = n & 31; return (n & ~31) + 16 * ((c >> 2) & 1) + 4 * (c >> 3) + (c & 3); }
;     const int dd = (n - 1024) & 127; return (n - dd) + ((((dd >> 4) & 3) << 5) | ((dd >> 6) << 4) | (dd & 15));
; __device__ __forceinline__ void tr_item_cu(const float* __restrict__ W, int K, int N, bf16* __restrict__ WT, const float* rowgain, int mode, LAS unsigned char* buf, int item, int wave, int lane) {
;     ...
;     for (int m = 0; m < 8; ++m) { const int row = 16 * wave + 2 * m + hr;
;         const u32x4 o = *(const LAS u32x4*)(buf + row * TCP + c * 16);
;         asm volatile("global_store_dwordx4 %0, %1, off sc1\n\ts_nop 1" :: "v"(WT + (size_t)row_map(mode, n0 + row) * K + k0 + 8 * c), "v"(o) : "memory"); }
.LBB0_169:
	v_ashrrev_i32_e32 v9, 31, v10
	v_mul_lo_u32 v12, s21, v10
	v_mul_lo_u32 v9, s20, v9
	v_mad_u64_u32 v[10:11], s[24:25], s20, v10, 0
	v_add3_u32 v11, v11, v9, v12
	v_lshl_add_u64 v[10:11], v[10:11], 1, v[6:7]
	s_waitcnt lgkmcnt(0)
	global_store_dwordx4 v[10:11], v[44:47], off sc1 nt
	s_nop 1
	s_cmp_lt_i32 s45, 1
	v_add_u32_e32 v8, s22, v105
	s_cbranch_scc1 .LBB0_174
	s_cmp_gt_i32 s45, 1
	s_cbranch_scc0 .LBB0_175
	s_cmp_eq_u32 s45, 2
	s_mov_b64 s[22:23], -1
	s_cbranch_scc0 .LBB0_173
	v_lshlrev_b32_e32 v9, 1, v8
	v_and_or_b32 v9, v9, s40, v116
	s_mov_b64 s[22:23], 0
